# GDN scan: next chunk's raw rows by LDS-DMA straight into LDS (no register prefetch / write-back), loop-top barrier dropped for chunks after the first
# baseline (speedup 1.0000x reference)
; DI void lds_barrier() { asm volatile("s_waitcnt lgkmcnt(0)" ::: "memory"); __builtin_amdgcn_s_barrier(); asm volatile("" ::: "memory"); }
; #define GD_WRITE() do { _Pragma("unroll") for (int j = 0; j < 6; ++j) { const int e = tid + 512 * j; if (e < 2800) *(LAS f32x4*)(RAW + 4 * e) = pre[j]; } \
;         if (tid < 32) { RAB[2 * tid] = pre_bt; RAB[2 * tid + 1] = pre_at; } } while (0)
; DI void gdn_scan_block(LAS unsigned char* lds, int c, const float* P, const GdnPar& pr, float* ORAW, int tid, int lane, int wave) {
;     ...
;     for (int cidx = 0; cidx < 64; ++cidx) {
;         GD_WRITE();
;         lds_barrier();
;         GD_DERIVE();
;         lds_barrier();
;         if (cidx + 1 < 64) GD_LOAD(cidx + 1);
.LBB0_889:
	s_waitcnt vmcnt(0)
	s_and_saveexec_b64 s[34:35], s[4:5]
	ds_write2_b32 v161, v108, v109 offset1:1
	s_or_b64 exec, exec, s[34:35]
	s_waitcnt lgkmcnt(0)
	s_barrier
	s_mov_b64 s[0:1], 0x30000
	v_lshl_add_u64 v[94:95], v[94:95], 0, s[0:1]
	v_lshl_add_u64 v[96:97], v[96:97], 0, s[0:1]
	s_add_i32 s50, s50, 32
	s_mov_b64 s[0:1], 0xa8000
	s_cmpk_eq_i32 s50, 0x800
	v_lshl_add_u64 v[98:99], v[98:99], 0, s[0:1]
	s_cbranch_scc1 .LBB0_951
.LBB0_890:
	s_cmp_lg_u32 s50, 0
	s_cbranch_scc1 .Lgdn_top_done
	s_and_saveexec_b64 s[34:35], s[10:11]
	s_cbranch_execnz .LBB0_915
	s_or_b64 exec, exec, s[34:35]
	s_and_saveexec_b64 s[34:35], s[12:13]
	s_cbranch_execnz .LBB0_916

; #define LAS __attribute__((address_space(3)))
; DI float siluf_(float x) { return x * frcp(1.f + __expf(-x)); }
; DI f32x4 gd_conv4(const LAS float* CW, const LAS float* RAW, int dt, int cc) {
;     f32x4 a = {0.f, 0.f, 0.f, 0.f};
; #pragma unroll
;     for (int j = 0; j < 4; ++j) a += *(const LAS f32x4*)(CW + j * 320 + cc) * *(const LAS f32x4*)(RAW + (dt + j) * 320 + cc);
; #pragma unroll
;     for (int i = 0; i < 4; ++i) a[i] = siluf_(a[i]);
;     return a;
; }
.Lgdn_top_done:
	ds_read_b128 v[72:75], v111
	ds_read_b128 v[76:79], v162
	s_waitcnt lgkmcnt(0)
	v_pk_fma_f32 v[80:81], v[74:75], v[78:79], 0 op_sel_hi:[1,1,0]
	v_pk_fma_f32 v[100:101], v[72:73], v[76:77], 0 op_sel_hi:[1,1,0]
	ds_read_b128 v[72:75], v111 offset:1280
	ds_read_b128 v[76:79], v162 offset:1280
	s_waitcnt lgkmcnt(0)
	v_pk_fma_f32 v[80:81], v[74:75], v[78:79], v[80:81]
	v_pk_fma_f32 v[100:101], v[72:73], v[76:77], v[100:101]
	ds_read_b128 v[72:75], v111 offset:2560
	ds_read_b128 v[76:79], v162 offset:2560
	s_waitcnt lgkmcnt(0)
	v_pk_fma_f32 v[80:81], v[74:75], v[78:79], v[80:81]
	v_pk_fma_f32 v[100:101], v[72:73], v[76:77], v[100:101]
	ds_read_b128 v[72:75], v111 offset:3840
	ds_read_b128 v[76:79], v162 offset:3840
	s_waitcnt lgkmcnt(0)
	v_pk_fma_f32 v[72:73], v[72:73], v[76:77], v[100:101]
	s_nop 0
	v_mul_f32_e32 v76, 0xbfb8aa3b, v72
	v_mul_f32_e32 v77, 0xbfb8aa3b, v73
	v_exp_f32_e32 v76, v76
	v_exp_f32_e32 v77, v77
	v_pk_fma_f32 v[74:75], v[74:75], v[78:79], v[80:81]
	v_add_f32_e32 v76, 1.0, v76
	v_add_f32_e32 v77, 1.0, v77
	v_rcp_f32_e32 v76, v76
	v_rcp_f32_e32 v77, v77
	s_nop 0
	v_pk_mul_f32 v[72:73], v[72:73], v[76:77]
	v_mul_f32_e32 v76, 0xbfb8aa3b, v74
	v_mul_f32_e32 v77, 0xbfb8aa3b, v75
	v_exp_f32_e32 v76, v76
	v_exp_f32_e32 v77, v77
	v_add_f32_e32 v76, 1.0, v76
	v_add_f32_e32 v77, 1.0, v77
	v_rcp_f32_e32 v76, v76
	v_rcp_f32_e32 v77, v77
	s_nop 0
	v_pk_mul_f32 v[74:75], v[74:75], v[76:77]
	ds_read_b128 v[76:79], v112
	ds_read_b128 v[100:103], v113
	s_waitcnt lgkmcnt(0)
	v_pk_fma_f32 v[80:81], v[78:79], v[102:103], 0 op_sel_hi:[1,1,0]
	v_pk_fma_f32 v[104:105], v[76:77], v[100:101], 0 op_sel_hi:[1,1,0]
	ds_read_b128 v[76:79], v112 offset:1280
	ds_read_b128 v[100:103], v113 offset:1280
	s_waitcnt lgkmcnt(0)
	v_pk_fma_f32 v[80:81], v[78:79], v[102:103], v[80:81]
	v_pk_fma_f32 v[104:105], v[76:77], v[100:101], v[104:105]
	ds_read_b128 v[76:79], v112 offset:2560
	ds_read_b128 v[100:103], v113 offset:2560
	s_waitcnt lgkmcnt(0)
	v_pk_fma_f32 v[80:81], v[78:79], v[102:103], v[80:81]
	v_pk_fma_f32 v[104:105], v[76:77], v[100:101], v[104:105]
	ds_read_b128 v[76:79], v112 offset:3840
	ds_read_b128 v[100:103], v113 offset:3840
	s_waitcnt lgkmcnt(0)
	v_pk_fma_f32 v[76:77], v[76:77], v[100:101], v[104:105]
	v_pk_fma_f32 v[78:79], v[78:79], v[102:103], v[80:81]
	v_mul_f32_e32 v80, 0xbfb8aa3b, v76
	v_mul_f32_e32 v81, 0xbfb8aa3b, v77
	v_exp_f32_e32 v80, v80
	v_exp_f32_e32 v81, v81
	ds_read_b128 v[100:103], v114
	ds_read_b128 v[190:193], v115
	v_add_f32_e32 v80, 1.0, v80
	v_add_f32_e32 v81, 1.0, v81
	v_rcp_f32_e32 v80, v80
	v_rcp_f32_e32 v81, v81
	s_waitcnt lgkmcnt(0)
	v_pk_fma_f32 v[104:105], v[100:101], v[190:191], 0 op_sel_hi:[1,1,0]
	v_pk_mul_f32 v[76:77], v[76:77], v[80:81]
	v_mul_f32_e32 v80, 0xbfb8aa3b, v78
	v_mul_f32_e32 v81, 0xbfb8aa3b, v79
	v_exp_f32_e32 v80, v80
	v_exp_f32_e32 v81, v81
	v_add_f32_e32 v80, 1.0, v80
	v_add_f32_e32 v81, 1.0, v81
	v_rcp_f32_e32 v80, v80
	v_rcp_f32_e32 v81, v81
	s_nop 0
	v_pk_mul_f32 v[78:79], v[78:79], v[80:81]
	v_pk_fma_f32 v[80:81], v[102:103], v[192:193], 0 op_sel_hi:[1,1,0]
	ds_read_b128 v[100:103], v114 offset:1280
	ds_read_b128 v[190:193], v115 offset:1280
	s_waitcnt lgkmcnt(0)
	v_pk_fma_f32 v[80:81], v[102:103], v[192:193], v[80:81]
	v_pk_fma_f32 v[104:105], v[100:101], v[190:191], v[104:105]
	ds_read_b128 v[100:103], v114 offset:2560
	ds_read_b128 v[190:193], v115 offset:2560
	s_waitcnt lgkmcnt(0)
	v_pk_fma_f32 v[80:81], v[102:103], v[192:193], v[80:81]
	v_pk_fma_f32 v[104:105], v[100:101], v[190:191], v[104:105]
	ds_read_b128 v[100:103], v114 offset:3840
	ds_read_b128 v[190:193], v115 offset:3840
	s_waitcnt lgkmcnt(0)
	v_pk_fma_f32 v[102:103], v[102:103], v[192:193], v[80:81]
	v_pk_fma_f32 v[80:81], v[100:101], v[190:191], v[104:105]
	s_nop 0
	v_mul_f32_e32 v100, 0xbfb8aa3b, v80
	v_mul_f32_e32 v101, 0xbfb8aa3b, v81
	v_exp_f32_e32 v100, v100
	v_exp_f32_e32 v101, v101
	v_add_f32_e32 v100, 1.0, v100
	v_add_f32_e32 v101, 1.0, v101
	v_rcp_f32_e32 v100, v100
	v_rcp_f32_e32 v101, v101
	s_nop 0
	v_pk_mul_f32 v[80:81], v[80:81], v[100:101]
	v_mul_f32_e32 v100, 0xbfb8aa3b, v102
	v_mul_f32_e32 v101, 0xbfb8aa3b, v103
	v_exp_f32_e32 v100, v100
	v_exp_f32_e32 v101, v101
	v_add_f32_e32 v100, 1.0, v100
	v_add_f32_e32 v101, 1.0, v101
	v_rcp_f32_e32 v100, v100
	v_rcp_f32_e32 v101, v101
	s_nop 0
	v_pk_mul_f32 v[100:101], v[102:103], v[100:101]
	ds_read_b128 v[102:105], v116
	ds_read_b128 v[190:193], v117
	s_waitcnt lgkmcnt(0)
	v_pk_fma_f32 v[130:131], v[104:105], v[192:193], 0 op_sel_hi:[1,1,0]
	v_pk_fma_f32 v[194:195], v[102:103], v[190:191], 0 op_sel_hi:[1,1,0]
	ds_read_b128 v[102:105], v116 offset:1280
	ds_read_b128 v[190:193], v117 offset:1280
	s_waitcnt lgkmcnt(0)
	v_pk_fma_f32 v[130:131], v[104:105], v[192:193], v[130:131]
	v_pk_fma_f32 v[194:195], v[102:103], v[190:191], v[194:195]
	ds_read_b128 v[102:105], v116 offset:2560
	ds_read_b128 v[190:193], v117 offset:2560
	s_waitcnt lgkmcnt(0)
	v_pk_fma_f32 v[130:131], v[104:105], v[192:193], v[130:131]
	v_pk_fma_f32 v[194:195], v[102:103], v[190:191], v[194:195]
	ds_read_b128 v[102:105], v116 offset:3840
	ds_read_b128 v[190:193], v117 offset:3840
	s_waitcnt lgkmcnt(0)
	v_pk_fma_f32 v[102:103], v[102:103], v[190:191], v[194:195]
	s_nop 0
	v_mul_f32_e32 v106, 0xbfb8aa3b, v102
	v_exp_f32_e32 v106, v106
	v_pk_fma_f32 v[104:105], v[104:105], v[192:193], v[130:131]
	ds_read_b128 v[190:193], v118
	ds_read_b128 v[194:197], v119
	v_add_f32_e32 v106, 1.0, v106
	v_rcp_f32_e32 v130, v106
	v_mul_f32_e32 v106, 0xbfb8aa3b, v103
	v_exp_f32_e32 v106, v106
	s_waitcnt lgkmcnt(0)
	v_pk_fma_f32 v[198:199], v[190:191], v[194:195], 0 op_sel_hi:[1,1,0]
	v_add_f32_e32 v106, 1.0, v106
	v_rcp_f32_e32 v131, v106
	v_mul_f32_e32 v106, 0xbfb8aa3b, v104
	v_exp_f32_e32 v106, v106
	v_pk_mul_f32 v[102:103], v[102:103], v[130:131]
	v_add_f32_e32 v106, 1.0, v106
	v_rcp_f32_e32 v130, v106
	v_mul_f32_e32 v106, 0xbfb8aa3b, v105
	v_exp_f32_e32 v106, v106
	s_nop 0
	v_add_f32_e32 v106, 1.0, v106
	v_rcp_f32_e32 v131, v106
	s_nop 0
	v_pk_mul_f32 v[104:105], v[104:105], v[130:131]
	v_pk_fma_f32 v[130:131], v[192:193], v[196:197], 0 op_sel_hi:[1,1,0]
	ds_read_b128 v[190:193], v118 offset:1280
	ds_read_b128 v[194:197], v119 offset:1280
	s_waitcnt lgkmcnt(0)
	v_pk_fma_f32 v[130:131], v[192:193], v[196:197], v[130:131]
	v_pk_fma_f32 v[198:199], v[190:191], v[194:195], v[198:199]
	ds_read_b128 v[190:193], v118 offset:2560
	ds_read_b128 v[194:197], v119 offset:2560
	s_waitcnt lgkmcnt(0)
	v_pk_fma_f32 v[130:131], v[192:193], v[196:197], v[130:131]
	v_pk_fma_f32 v[198:199], v[190:191], v[194:195], v[198:199]
	ds_read_b128 v[190:193], v118 offset:3840
	ds_read_b128 v[194:197], v119 offset:3840
	s_waitcnt lgkmcnt(0)
	v_pk_fma_f32 v[190:191], v[190:191], v[194:195], v[198:199]
	s_nop 0
	v_mul_f32_e32 v106, 0xbfb8aa3b, v190
	v_exp_f32_e32 v106, v106
	v_pk_fma_f32 v[130:131], v[192:193], v[196:197], v[130:131]
	v_mov_b32_e32 v196, v75
	v_mov_b32_e32 v197, v79
	v_add_f32_e32 v106, 1.0, v106
	v_rcp_f32_e32 v194, v106
	v_mul_f32_e32 v106, 0xbfb8aa3b, v191
	v_exp_f32_e32 v106, v106
	v_pk_mul_f32 v[196:197], v[196:197], v[196:197]
	v_add_f32_e32 v106, 1.0, v106
	v_rcp_f32_e32 v195, v106
	v_mul_f32_e32 v106, 0xbfb8aa3b, v130
	v_exp_f32_e32 v106, v106
	v_pk_mul_f32 v[190:191], v[190:191], v[194:195]
	v_mov_b32_e32 v194, v73
	v_add_f32_e32 v106, 1.0, v106
	v_rcp_f32_e32 v192, v106
	v_mul_f32_e32 v106, 0xbfb8aa3b, v131
	v_exp_f32_e32 v106, v106
	v_mov_b32_e32 v195, v77
	v_pk_mul_f32 v[194:195], v[194:195], v[194:195]
	v_add_f32_e32 v106, 1.0, v106
	v_rcp_f32_e32 v193, v106
	s_nop 0
	v_pk_mul_f32 v[192:193], v[130:131], v[192:193]
	v_mov_b32_e32 v130, v72
	v_mov_b32_e32 v131, v76
	v_pk_fma_f32 v[130:131], v[130:131], v[130:131], v[194:195]
	v_mov_b32_e32 v194, v74
	v_mov_b32_e32 v195, v78
	v_pk_fma_f32 v[194:195], v[194:195], v[194:195], v[196:197]
	v_mov_b32_e32 v196, v101
	v_pk_add_f32 v[130:131], v[130:131], v[194:195]
	v_mov_b32_e32 v194, v81
	v_mov_b32_e32 v195, v103
	v_add_f32_e32 v106, v130, v131
	v_mov_b32_e32 v130, v80
	v_mov_b32_e32 v131, v102
	v_pk_mul_f32 v[194:195], v[194:195], v[194:195]
	v_mov_b32_e32 v197, v105
	v_pk_fma_f32 v[130:131], v[130:131], v[130:131], v[194:195]
	v_mov_b32_e32 v194, v100
	v_mov_b32_e32 v195, v104
	v_pk_mul_f32 v[196:197], v[196:197], v[196:197]
	v_add_f32_dpp v106, v106, v106 quad_perm:[1,0,3,2] row_mask:0xf bank_mask:0xf bound_ctrl:1
	v_pk_fma_f32 v[194:195], v[194:195], v[194:195], v[196:197]
	s_nop 0
	v_pk_add_f32 v[130:131], v[130:131], v[194:195]
	v_add_f32_dpp v106, v106, v106 quad_perm:[2,3,0,1] row_mask:0xf bank_mask:0xf bound_ctrl:1
	v_add_f32_e32 v128, v130, v131
	s_nop 0
	v_add_f32_dpp v106, v106, v106 row_half_mirror row_mask:0xf bank_mask:0xf bound_ctrl:1
	v_add_f32_dpp v128, v128, v128 quad_perm:[1,0,3,2] row_mask:0xf bank_mask:0xf bound_ctrl:1
	s_nop 0
	v_add_f32_dpp v106, v106, v106 row_ror:8 row_mask:0xf bank_mask:0xf bound_ctrl:1
	v_add_f32_dpp v128, v128, v128 quad_perm:[2,3,0,1] row_mask:0xf bank_mask:0xf bound_ctrl:1
	v_add_f32_e32 v106, 0x358637bd, v106
	v_rsq_f32_e32 v106, v106
	v_add_f32_dpp v128, v128, v128 row_half_mirror row_mask:0xf bank_mask:0xf bound_ctrl:1
	v_mul_f32_e32 v106, 0x3db504f3, v106
	s_nop 0
	v_add_f32_dpp v128, v128, v128 row_ror:8 row_mask:0xf bank_mask:0xf bound_ctrl:1
	v_add_f32_e32 v128, 0x358637bd, v128
	v_rsq_f32_e32 v128, v128
	v_pk_mul_f32 v[74:75], v[74:75], v[106:107] op_sel_hi:[1,0]
	v_pk_mul_f32 v[72:73], v[72:73], v[106:107] op_sel_hi:[1,0]
	v_pk_mul_f32 v[78:79], v[78:79], v[106:107] op_sel_hi:[1,0]
	v_pk_mul_f32 v[76:77], v[76:77], v[106:107] op_sel_hi:[1,0]
	ds_write_b128 v120, v[72:75]
	v_pk_mul_f32 v[196:197], v[100:101], v[128:129] op_sel_hi:[1,0]
	v_pk_mul_f32 v[194:195], v[80:81], v[128:129] op_sel_hi:[1,0]
	v_pk_mul_f32 v[104:105], v[104:105], v[128:129] op_sel_hi:[1,0]
	v_pk_mul_f32 v[102:103], v[102:103], v[128:129] op_sel_hi:[1,0]
	v_cvt_pk_bf16_f32 v72, v72, v73
	v_cvt_pk_bf16_f32 v73, v74, v75
	v_cvt_pk_bf16_f32 v74, v76, v77
	v_cvt_pk_bf16_f32 v75, v78, v79
	v_add_u32_e32 v80, s83, v122
	ds_write_b128 v120, v[76:79] offset:16
	ds_write_b128 v120, v[194:197] offset:16896
	ds_write_b128 v120, v[102:105] offset:16912
	ds_write_b128 v121, v[190:193] offset:33792
	v_cvt_pk_bf16_f32 v76, v194, v195
	v_cvt_pk_bf16_f32 v77, v196, v197
	v_cvt_pk_bf16_f32 v78, v102, v103
	v_cvt_pk_bf16_f32 v79, v104, v105
	ds_write_b128 v80, v[72:75]
	v_add_u32_e32 v72, s46, v122
	ds_write_b128 v72, v[76:79]
	s_and_saveexec_b64 s[48:49], s[6:7]
	s_cbranch_execz .LBB0_900
	ds_read_b32 v72, v124
	s_mov_b32 s0, 0xbfb8aa3b
	s_waitcnt lgkmcnt(0)
	v_add_f32_e32 v72, v107, v72
	v_mul_f32_e64 v73, |v72|, s0
	v_exp_f32_e32 v73, v73
	s_mov_b32 s0, 0x800000
	v_max_f32_e32 v72, 0, v72
	v_add_f32_e32 v73, 1.0, v73
	v_cmp_gt_f32_e32 vcc, s0, v73
	s_mov_b32 s0, 0x3f317217
	s_nop 0
	v_cndmask_b32_e64 v74, 0, 32, vcc
	v_ldexp_f32 v73, v73, v74
	v_log_f32_e32 v73, v73
	s_nop 0
	v_mul_f32_e32 v74, 0x3f317217, v73
	v_fma_f32 v74, v73, s0, -v74
	v_fmac_f32_e32 v74, 0x3377d1cf, v73
	s_mov_b32 s0, 0x7f800000
	v_fmac_f32_e32 v74, 0x3f317217, v73
	v_cmp_lt_f32_e64 s[34:35], |v73|, s0
	s_nop 1
	v_cndmask_b32_e64 v73, v73, v74, s[34:35]
	v_cndmask_b32_e32 v74, 0, v243, vcc
	v_sub_f32_e32 v73, v73, v74
	v_add_f32_e32 v72, v72, v73
	v_mul_f32_e64 v72, v72, -v110
	ds_write_b32 v163, v72 offset:41984
	ds_read_b32 v72, v123
	s_waitcnt lgkmcnt(0)
	v_mul_f32_e32 v72, 0xbfb8aa3b, v72
	v_exp_f32_e32 v72, v72
	s_nop 0
	v_add_f32_e32 v72, 1.0, v72
	v_rcp_f32_e32 v72, v72
	ds_write_b32 v163, v72 offset:41988

.LBB0_921:
	s_waitcnt vmcnt(0)
	s_movk_i32 s33, 0x5400
	s_and_saveexec_b64 s[34:35], s[10:11]
	v_add_u32_e32 v8, s50, v149
	v_mov_b32_e32 v9, v129
	v_lshl_add_u64 v[0:1], s[42:43], 0, v[8:9]
	v_mad_u64_u32 v[2:3], s[0:1], v0, s33, v[82:83]
	v_mad_i32_i24 v3, v1, s33, v3
	v_readfirstlane_b32 s0, v155
	s_mov_b32 m0, s0
	s_nop 0
	global_load_lds_dwordx4 v[2:3], off
	s_or_b64 exec, exec, s[34:35]
	s_and_saveexec_b64 s[34:35], s[12:13]
	v_add_u32_e32 v8, s50, v150
	v_mov_b32_e32 v9, v129
	v_lshl_add_u64 v[0:1], s[42:43], 0, v[8:9]
	v_mad_u64_u32 v[2:3], s[0:1], v0, s33, v[84:85]
	v_mad_i32_i24 v3, v1, s33, v3
	v_readfirstlane_b32 s0, v156
	s_mov_b32 m0, s0
	s_nop 0
	global_load_lds_dwordx4 v[2:3], off
	s_or_b64 exec, exec, s[34:35]
	s_and_saveexec_b64 s[34:35], s[14:15]
	v_add_u32_e32 v8, s50, v151
	v_mov_b32_e32 v9, v129
	v_lshl_add_u64 v[0:1], s[42:43], 0, v[8:9]
	v_mad_u64_u32 v[2:3], s[0:1], v0, s33, v[86:87]
	v_mad_i32_i24 v3, v1, s33, v3
	v_readfirstlane_b32 s0, v157
	s_mov_b32 m0, s0
	s_nop 0
	global_load_lds_dwordx4 v[2:3], off
	s_or_b64 exec, exec, s[34:35]
	s_and_saveexec_b64 s[34:35], s[16:17]
	v_add_u32_e32 v8, s50, v152
	v_mov_b32_e32 v9, v129
	v_lshl_add_u64 v[0:1], s[42:43], 0, v[8:9]
	v_mad_u64_u32 v[2:3], s[0:1], v0, s33, v[88:89]
	v_mad_i32_i24 v3, v1, s33, v3
	v_readfirstlane_b32 s0, v158
	s_mov_b32 m0, s0
	s_nop 0
	global_load_lds_dwordx4 v[2:3], off
	s_or_b64 exec, exec, s[34:35]
	s_and_saveexec_b64 s[34:35], s[18:19]
	v_add_u32_e32 v8, s50, v153
	v_mov_b32_e32 v9, v129
	v_lshl_add_u64 v[0:1], s[42:43], 0, v[8:9]
	v_mad_u64_u32 v[2:3], s[0:1], v0, s33, v[90:91]
	v_mad_i32_i24 v3, v1, s33, v3
	v_readfirstlane_b32 s0, v159
	s_mov_b32 m0, s0
	s_nop 0
	global_load_lds_dwordx4 v[2:3], off
	s_or_b64 exec, exec, s[34:35]
	s_and_saveexec_b64 s[34:35], s[20:21]
	v_add_u32_e32 v8, s50, v154
	v_mov_b32_e32 v9, v129
	v_lshl_add_u64 v[0:1], s[42:43], 0, v[8:9]
	v_mad_u64_u32 v[2:3], s[0:1], v0, s33, v[92:93]
	v_mad_i32_i24 v3, v1, s33, v3
	v_readfirstlane_b32 s0, v160
	s_mov_b32 m0, s0
	s_nop 0
	global_load_lds_dwordx4 v[2:3], off
	s_or_b64 exec, exec, s[34:35]
	s_and_saveexec_b64 s[34:35], s[4:5]
	s_cbranch_execz .LBB0_947
	v_lshl_add_u64 v[72:73], s[40:41], 0, v[98:99]
	v_add_co_u32_e32 v72, vcc, 0x18aac000, v72
	s_nop 1
	v_addc_co_u32_e32 v73, vcc, 0, v73, vcc
	global_load_dword v108, v[72:73], off offset:2048
	global_load_dword v109, v[72:73], off offset:2096
